# same-XCD group barrier: acquire drops only this CU's L1 (buffer_inv sc0 instead of agent-scope sc1); the shared L2 of the XCD stays valid
# speedup vs baseline: 1.0220x; 1.0220x over previous
.LBB0_944:
	buffer_inv sc0
	s_waitcnt vmcnt(0)
